# bundle19 + per-unit tile decode in P1/P4/P10 uses shifts for the fixed group size 8 (removes the v_rcp/readfirstlane division chain from the unit boundary)
# speedup vs baseline: 1.0064x; 1.0021x over previous
.LBB0_290:
	s_add_i32 s66, s66, 1
	s_mul_i32 s2, s66, s67
	s_mul_hi_u32 s3, s66, s33
	s_add_i32 s3, s3, s2
	s_mul_i32 s2, s66, s33
	s_add_u32 s14, s2, s18
	s_addc_u32 s15, s3, s31
	v_cmp_gt_i64_e32 vcc, s[14:15], v[144:145]
	v_cmp_lt_i64_e64 s[2:3], s[14:15], v[142:143]
	s_cbranch_vccnz .LBB0_292
	s_ashr_i32 s10, s14, 31
	s_lshr_b32 s10, s10, 29
	s_add_i32 s10, s14, s10
	s_ashr_i32 s11, s10, 3
	s_and_b32 s10, s10, -8
	s_sub_i32 s10, s14, s10
	s_cmp_lt_i32 s10, 0
	s_cselect_b32 s12, s56, 0x2c0
	s_mul_i32 s10, s10, s12
	s_add_i32 s10, s10, s11
	s_mul_hi_i32 s11, s10, 0x2e8ba2e9
	s_lshr_b32 s12, s11, 31
	s_ashr_i32 s11, s11, 6
	s_add_i32 s11, s11, s12
	s_lshl_b32 s12, s11, 3
	s_mulk_i32 s11, 0x160
	s_sub_i32 s11, s10, s11
	s_lshr_b32 s10, s11, 3
	s_and_b32 s11, s11, 7
	s_add_i32 s12, s12, s11

.LBB0_466:
	s_add_i32 s22, s22, 1
	s_mul_i32 s4, s22, s42
	s_mul_hi_u32 s5, s22, s33
	s_add_i32 s5, s5, s4
	s_mul_i32 s4, s22, s33
	s_add_u32 s70, s4, s88
	s_addc_u32 s71, s5, s43
	v_mov_b64_e32 v[2:3], 0x1480
	v_cmp_lt_i64_e64 s[4:5], s[70:71], v[2:3]
	v_mov_b64_e32 v[2:3], 0x147f
	v_cmp_gt_i64_e32 vcc, s[70:71], v[2:3]
	s_mov_b32 s29, s10
	s_cbranch_vccnz .LBB0_468
	s_ashr_i32 s10, s70, 31
	s_lshr_b32 s10, s10, 29
	s_add_i32 s10, s70, s10
	s_ashr_i32 s11, s10, 3
	s_and_b32 s10, s10, -8
	s_sub_i32 s10, s70, s10
	s_cmp_lt_i32 s10, 0
	s_movk_i32 s68, 0x291
	s_cselect_b32 s68, s68, 0x290
	s_mul_i32 s10, s10, s68
	s_add_i32 s10, s10, s11
	s_mul_hi_i32 s11, s10, 0x63e7063f
	s_lshr_b32 s68, s11, 31
	s_ashr_i32 s11, s11, 7
	s_add_i32 s11, s11, s68
	s_lshl_b32 s69, s11, 3
	s_mulk_i32 s11, 0x148
	s_sub_i32 s10, s10, s11
	s_lshr_b32 s68, s10, 3
	s_and_b32 s10, s10, 7
	s_add_i32 s10, s69, s10

.LBB0_1476:
	s_add_i32 s52, s52, 1
	s_mul_i32 s2, s52, s53
	s_mul_hi_u32 s3, s52, s33
	s_add_i32 s3, s3, s2
	s_mul_i32 s2, s52, s33
	s_add_u32 s6, s2, s18
	s_addc_u32 s7, s3, s42
	v_cmp_gt_i64_e32 vcc, s[6:7], v[152:153]
	s_mov_b32 s58, s10
	v_cmp_lt_i64_e64 s[2:3], s[6:7], v[150:151]
	s_cbranch_vccnz .LBB0_1478
	s_ashr_i32 s7, s6, 31
	s_lshr_b32 s7, s7, 29
	s_add_i32 s7, s6, s7
	s_ashr_i32 s9, s7, 3
	s_and_b32 s7, s7, -8
	s_sub_i32 s6, s6, s7
	s_cmp_lt_i32 s6, 0
	s_cselect_b32 s7, s43, 0x2c0
	s_mul_i32 s6, s6, s7
	s_add_i32 s6, s6, s9
	s_mul_hi_i32 s7, s6, 0x2e8ba2e9
	s_lshr_b32 s9, s7, 31
	s_ashr_i32 s7, s7, 6
	s_add_i32 s7, s7, s9
	s_lshl_b32 s9, s7, 3
	s_mulk_i32 s7, 0x160
	s_sub_i32 s6, s6, s7
	s_lshr_b32 s36, s6, 3
	s_and_b32 s6, s6, 7
	s_add_i32 s10, s9, s6
